# pass128: global loads spread one per MFMA gap (unconditional clamped tile), simple tid-based half roles, next-tile LDS addresses computed in the softmax tail
# speedup vs baseline: 1.0599x; 1.0150x over previous
; #define LAS __attribute__((address_space(3)))
; template <int DV> ...
;     ...
;     for (int t = 0; t < nt; ++t) {
;         const int k0 = (t < n0) ? (s0a + (t << 6)) : (s1a + ((t - n0) << 6));
;         const bool more = (t + 1 < nt);
;         if (more) {
;             const int k1 = (t + 1 < n0) ? (s0a + ((t + 1) << 6)) : (s1a + ((t + 1 - n0) << 6));
;             kr = *(const u32x4*)(kg + (size_t)k1 * kpitch); vr0 = *(const u32x4*)(vg + k1);
;             if (DV == 128) vr1 = *(const u32x4*)(vg + (size_t)64 * NKV + k1);
;         }
;         const LAS unsigned char* Kl = lds + (t & 1) * ABUFB;
;         const LAS unsigned char* Vl = Kl + KBUFB;
;         const bool masked = win && (t < n0);
;         const bool skip = masked && ((k0 + 63 < qw0 - 128) || (k0 > qw0 + 31 + 128));
;         if (!skip) {
;             f32x16 p0, p1;
;             {
;                 bf16x8 kf[8];
; #pragma unroll
;                 for (int d0 = 0; d0 < 4; ++d0) {
;                     kf[2 * d0] = *(const LAS bf16x8*)(Kl + (r32 * KP + 16 * d0 + 8 * hi) * 2);
;                     kf[2 * d0 + 1] = *(const LAS bf16x8*)(Kl + ((32 + r32) * KP + 16 * d0 + 8 * hi) * 2);
;                 }
;                 __builtin_amdgcn_sched_barrier(0);
;                 p0 = __builtin_amdgcn_mfma_f32_32x32x16_bf16(kf[0], qf[0], negm, 0, 0, 0); p1 = __builtin_amdgcn_mfma_f32_32x32x16_bf16(kf[1], qf[0], negm, 0, 0, 0);
; #pragma unroll
;                 for (int d0 = 1; d0 < 4; ++d0) { p0 = __builtin_amdgcn_mfma_f32_32x32x16_bf16(kf[2 * d0], qf[d0], p0, 0, 0, 0); p1 = __builtin_amdgcn_mfma_f32_32x32x16_bf16(kf[2 * d0 + 1], qf[d0], p1, 0, 0, 0); }
;     ...
;             if (DV == 128) {
;                 bf16x8 vfb[8];
; #pragma unroll
;                 for (int db = 2; db < 4; ++db)
; #pragma unroll
;                     for (int c = 0; c < 4; ++c) vfb[(db - 2) * 4 + c] = *(const LAS bf16x8*)(Vl + ((32 * db + r32) * VP + 16 * c + 8 * hi) * 2);
; #pragma unroll
;                 for (int db = 0; db < 2; ++db)
; #pragma unroll
;                     for (int c = 0; c < 4; ++c) {
;                         o[db] = __builtin_amdgcn_mfma_f32_32x32x16_bf16(vfa[db * 4 + c], pk[c], o[db], 0, 0, 0);
;                     }
;                 __builtin_amdgcn_sched_barrier(0);
; #pragma unroll
;                 for (int db = 2; db < DV / 32; ++db)
; #pragma unroll
;                     for (int c = 0; c < 4; ++c) {
.Lpa_pre_done:
	v_readfirstlane_b32 s25, v253
	s_lshr_b32 s25, s25, 8
	s_mov_b32 s22, 0
	s_cmp_eq_u32 s25, 0
	s_cbranch_scc1 .Lpa_X
	s_barrier
.Lpa_X:
	s_setprio 1
	s_and_b32 s4, s22, 1
	s_mul_i32 s23, s4, 0x6c00
	s_sub_i32 s24, 0x6c00, s23
	v_add_u32_e32 v199, s23, v194
	s_add_i32 s3, s22, 1
	s_mul_hi_u32 s4, s3, 0x55555556
	s_mul_i32 s4, s4, 3
	s_sub_i32 s4, s3, s4
	s_mul_i32 s5, s4, 0x6c00
	v_add_u32_e32 v218, s24, v192
	v_add_u32_e32 v219, s5, v193
	s_branch .Lpa_Xfirst
.Lpa_X2:
	s_setprio 1
	s_cmp_ge_i32 s22, s26
	s_cbranch_scc1 .Lpa_Xlast
	s_waitcnt lgkmcnt(11)
	v_mfma_f32_32x32x16_bf16 v[2:17], v[82:85], v[200:203], v[2:17]
	ds_read_b128 v[158:161], v197 offset:23040
	s_waitcnt lgkmcnt(11)
	v_mfma_f32_32x32x16_bf16 v[2:17], v[86:89], v[204:207], v[2:17]
	ds_read_b128 v[162:165], v197 offset:23072
	s_waitcnt lgkmcnt(11)
	v_mfma_f32_32x32x16_bf16 v[2:17], v[90:93], v[210:213], v[2:17]
	ds_read_b128 v[166:169], v197 offset:23104
	s_waitcnt lgkmcnt(11)
	v_mfma_f32_32x32x16_bf16 v[2:17], v[94:97], v[214:217], v[2:17]
	ds_read_b128 v[170:173], v197 offset:23136
	s_waitcnt vmcnt(0)
	s_waitcnt lgkmcnt(11)
	v_mfma_f32_32x32x16_bf16 v[18:33], v[98:101], v[200:203], v[18:33]
	ds_write_b128 v218, v[130:133]
	s_waitcnt lgkmcnt(11)
	v_mfma_f32_32x32x16_bf16 v[18:33], v[102:105], v[204:207], v[18:33]
	ds_write_b128 v219, v[134:137] offset:9216
	s_waitcnt lgkmcnt(11)
	v_mfma_f32_32x32x16_bf16 v[18:33], v[106:109], v[210:213], v[18:33]
	ds_write_b128 v219, v[138:141] offset:18432
	s_waitcnt lgkmcnt(11)
	v_mfma_f32_32x32x16_bf16 v[18:33], v[110:113], v[214:217], v[18:33]
	s_add_i32 s3, s22, 2
	s_add_i32 s4, s26, -1
	s_min_i32 s3, s3, s4
	s_cmp_lt_i32 s3, s1
	s_cselect_b32 s4, 0, s1
	s_cselect_b32 s5, s94, 0x2000
	s_sub_i32 s4, s3, s4
	s_lshl_b32 s4, s4, 6
	s_add_i32 s4, s5, s4
	s_ashr_i32 s5, s4, 31
	s_lshl_b64 s[30:31], s[4:5], 10
	v_lshl_add_u64 v[218:219], v[180:181], 0, s[30:31]
	s_lshl_b64 s[30:31], s[4:5], 1
	v_lshl_add_u64 v[220:221], v[182:183], 0, s[30:31]
	s_waitcnt lgkmcnt(10)
	v_mfma_f32_32x32x16_bf16 v[50:65], v[142:145], v[200:203], v[50:65]
	ds_read_b128 v[142:145], v199
	global_load_dwordx4 v[130:133], v[218:219], off
	s_waitcnt lgkmcnt(10)
	v_mfma_f32_32x32x16_bf16 v[50:65], v[146:149], v[204:207], v[50:65]
	ds_read_b128 v[146:149], v199 offset:4608
	global_load_dwordx4 v[134:137], v[220:221], off
	s_waitcnt lgkmcnt(10)
	v_mfma_f32_32x32x16_bf16 v[50:65], v[150:153], v[210:213], v[50:65]
	ds_read_b128 v[150:153], v199 offset:32
	v_lshl_add_u64 v[218:219], v[186:187], 0, s[30:31]
	s_waitcnt lgkmcnt(10)
	v_mfma_f32_32x32x16_bf16 v[50:65], v[154:157], v[214:217], v[50:65]
	ds_read_b128 v[154:157], v199 offset:4640
	global_load_dwordx4 v[138:141], v[218:219], off
	s_waitcnt lgkmcnt(10)
	v_mfma_f32_32x32x16_bf16 v[34:49], v[158:161], v[200:203], v[34:49]
	ds_read_b128 v[158:161], v199 offset:64
	s_waitcnt lgkmcnt(10)
	v_mfma_f32_32x32x16_bf16 v[34:49], v[162:165], v[204:207], v[34:49]
	ds_read_b128 v[162:165], v199 offset:4672
	s_waitcnt lgkmcnt(10)
	v_mfma_f32_32x32x16_bf16 v[34:49], v[166:169], v[210:213], v[34:49]
	ds_read_b128 v[166:169], v199 offset:96
	s_waitcnt lgkmcnt(10)
	v_mfma_f32_32x32x16_bf16 v[34:49], v[170:173], v[214:217], v[34:49]
	ds_read_b128 v[170:173], v199 offset:4704
	s_waitcnt lgkmcnt(7)
	v_mfma_f32_32x32x16_bf16 v[98:113], v[142:145], v[126:129], v[66:81]
	s_waitcnt lgkmcnt(6)
	v_mfma_f32_32x32x16_bf16 v[82:97], v[146:149], v[126:129], v[66:81]
	s_waitcnt lgkmcnt(5)
	v_mfma_f32_32x32x16_bf16 v[98:113], v[150:153], v[122:125], v[98:113]
	s_waitcnt lgkmcnt(4)
	v_mfma_f32_32x32x16_bf16 v[82:97], v[154:157], v[122:125], v[82:97]
	s_waitcnt lgkmcnt(3)
	v_mfma_f32_32x32x16_bf16 v[98:113], v[158:161], v[118:121], v[98:113]
	s_waitcnt lgkmcnt(2)
	v_mfma_f32_32x32x16_bf16 v[82:97], v[162:165], v[118:121], v[82:97]
	s_waitcnt lgkmcnt(1)
	v_mfma_f32_32x32x16_bf16 v[98:113], v[166:169], v[114:117], v[98:113]
	s_waitcnt lgkmcnt(0)
	v_mfma_f32_32x32x16_bf16 v[82:97], v[170:173], v[114:117], v[82:97]
	s_barrier
	s_branch .Lpa_Y

; template <int DV> ...
;     ...
;             lrun += rs0 + rs1;
;             bf16x8 pk[4];
;             { u32x4 w;
;               w.x = cvtpk(p0[0], p0[1]); w.y = cvtpk(p0[2], p0[3]); w.z = cvtpk(p0[4], p0[5]); w.w = cvtpk(p0[6], p0[7]); pk[0] = __builtin_bit_cast(bf16x8, w);
;               w.x = cvtpk(p0[8], p0[9]); w.y = cvtpk(p0[10], p0[11]); w.z = cvtpk(p0[12], p0[13]); w.w = cvtpk(p0[14], p0[15]); pk[1] = __builtin_bit_cast(bf16x8, w);
;               w.x = cvtpk(p1[0], p1[1]); w.y = cvtpk(p1[2], p1[3]); w.z = cvtpk(p1[4], p1[5]); w.w = cvtpk(p1[6], p1[7]); pk[2] = __builtin_bit_cast(bf16x8, w);
;               w.x = cvtpk(p1[8], p1[9]); w.y = cvtpk(p1[10], p1[11]); w.z = cvtpk(p1[12], p1[13]); w.w = cvtpk(p1[14], p1[15]); pk[3] = __builtin_bit_cast(bf16x8, w); }
;             __builtin_amdgcn_sched_barrier(0);
;             if (DV == 128) {
;                 bf16x8 vfb[8];
; #pragma unroll
;                 for (int db = 2; db < 4; ++db)
; #pragma unroll
;                     for (int c = 0; c < 4; ++c) vfb[(db - 2) * 4 + c] = *(const LAS bf16x8*)(Vl + ((32 * db + r32) * VP + 16 * c + 8 * hi) * 2);
; #pragma unroll
;                 for (int db = 0; db < 2; ++db)
; #pragma unroll
;                     for (int c = 0; c < 4; ++c) {
;                         o[db] = __builtin_amdgcn_mfma_f32_32x32x16_bf16(vfa[db * 4 + c], pk[c], o[db], 0, 0, 0);
;                     }
;                 __builtin_amdgcn_sched_barrier(0);
; #pragma unroll
;                 for (int db = 2; db < DV / 32; ++db)
; #pragma unroll
;                     for (int c = 0; c < 4; ++c) {
;                         o[db] = __builtin_amdgcn_mfma_f32_32x32x16_bf16(vfb[(db - 2) * 4 + c], pk[c], o[db], 0, 0, 0);
;                     }
;             } else {
; #pragma unroll
;                 for (int db = 0; db < 2; ++db)
; #pragma unroll
;                     for (int c = 0; c < 4; ++c) {
;                         o[db] = __builtin_amdgcn_mfma_f32_32x32x16_bf16(vfa[db * 4 + c], pk[c], o[db], 0, 0, 0);
;                     }
;             }
;             __builtin_amdgcn_sched_barrier(0);
;         }
;         if (more) {
;             const unsigned bo = ((t + 1) & 1) * ABUFB;
;             *(LAS u32x4*)(lds + bo + kst) = kr;
;             *(LAS u32x4*)(lds + bo + vst) = vr0;
;             if (DV == 128) *(LAS u32x4*)(lds + bo + vst + 64 * VP * 2) = vr1;
;         }
.Lpa_tail:
	v_add_f32_e32 v189, v189, v198
	s_mul_hi_u32 s4, s22, 0x55555556
	s_mul_i32 s4, s4, 3
	s_sub_i32 s4, s22, s4
	s_mul_i32 s4, s4, 0x6c00
	v_add3_u32 v197, s4, v0, v196
	ds_read_b128 v[82:85], v197 offset:9216
	ds_read_b128 v[86:89], v197 offset:9248
	ds_read_b128 v[90:93], v197 offset:9280
	ds_read_b128 v[94:97], v197 offset:9312
	ds_read_b128 v[98:101], v197 offset:13824
	ds_read_b128 v[102:105], v197 offset:13856
	ds_read_b128 v[106:109], v197 offset:13888
	ds_read_b128 v[110:113], v197 offset:13920
	ds_read_b128 v[142:145], v197 offset:18432
	ds_read_b128 v[146:149], v197 offset:18464
	ds_read_b128 v[150:153], v197 offset:18496
	ds_read_b128 v[154:157], v197 offset:18528
	s_add_i32 s22, s22, 1
	s_and_b32 s4, s22, 1
	s_mul_i32 s23, s4, 0x6c00
	s_sub_i32 s24, 0x6c00, s23
	v_add_u32_e32 v199, s23, v194
	s_add_i32 s3, s22, 1
	s_mul_hi_u32 s4, s3, 0x55555556
	s_mul_i32 s4, s4, 3
	s_sub_i32 s4, s3, s4
	s_mul_i32 s5, s4, 0x6c00
	v_add_u32_e32 v218, s24, v192
	v_add_u32_e32 v219, s5, v193
	s_barrier
	s_branch .Lpa_X2
